# v35 + grid barrier: non-leader workgroups poll the cross-XCD generation word directly (one release hop less)
# baseline (speedup 1.0000x reference)
.LBB0_211:
	v_readlane_b32 s6, v254, 8
	s_lshl_b32 s6, s6, 8
	v_readlane_b32 s8, v254, 6
	v_readlane_b32 s9, v254, 7
	s_add_u32 s6, s8, s6
	s_addc_u32 s7, s9, 0
	v_mov_b32_e32 v1, 0x1000
	v_mov_b32_e32 v3, 1
	global_atomic_add v3, v1, v3, s[6:7] offset:1024 sc0
	v_cvt_f32_u32_e32 v1, v2
	v_sub_u32_e32 v4, 0, v2
	s_add_u32 s6, s6, 0x2400
	s_addc_u32 s7, s7, 0
	v_rcp_iflag_f32_e32 v1, v1
	s_nop 0
	v_mul_f32_e32 v1, 0x4f7ffffe, v1
	v_cvt_u32_f32_e32 v1, v1
	v_mul_lo_u32 v4, v4, v1
	v_mul_hi_u32 v4, v1, v4
	v_add_u32_e32 v1, v1, v4
	s_waitcnt vmcnt(0)
	v_mul_hi_u32 v1, v3, v1
	v_mul_lo_u32 v4, v1, v2
	v_sub_u32_e32 v4, v3, v4
	v_add_u32_e32 v5, 1, v1
	v_cmp_ge_u32_e32 vcc, v4, v2
	v_add_u32_e32 v3, 1, v3
	s_nop 0
	v_cndmask_b32_e32 v1, v1, v5, vcc
	v_sub_u32_e32 v5, v4, v2
	v_cndmask_b32_e32 v4, v4, v5, vcc
	v_add_u32_e32 v5, 1, v1
	v_cmp_ge_u32_e32 vcc, v4, v2
	s_nop 1
	v_cndmask_b32_e32 v1, v1, v5, vcc
	v_mul_lo_u32 v4, v2, v1
	v_add_u32_e32 v2, v4, v2
	v_cmp_ne_u32_e32 vcc, v3, v2
	s_and_saveexec_b64 s[8:9], vcc
	s_xor_b64 s[8:9], exec, s[8:9]
	s_cbranch_execz .LBB0_225
	s_waitcnt lgkmcnt(0)
	v_mov_b32_e32 v0, 0
	s_add_u32 s6, s96, 0x83500
	s_addc_u32 s7, s97, 0
	global_load_dword v2, v0, s[6:7] sc1
	s_waitcnt vmcnt(0)
	v_cmp_eq_u32_e32 vcc, v2, v1
	s_and_saveexec_b64 s[10:11], vcc
	s_cbranch_execz .LBB0_224
	s_mov_b32 s22, 1
	s_mov_b64 s[12:13], 0
	s_branch .LBB0_215
